# adds: down-GEMM residual epilogue software-pipelined (8 X loads in flight instead of 32 serialized load-wait-store round trips)
# baseline (speedup 1.0000x reference)
; DI void gemm_phase(const GemmArgs& g, char* shm_c) {
;     ...
;       const float* gp = g.gate + (brow < SEQ ? 0 : 1) * 6144 + bcol + wc * 32 + 4 * fq;
;       f32x4 gvv[2][2];
; #pragma unroll
;       for (int bj = 0; bj < 2; ++bj)
; #pragma unroll
;         for (int n = 0; n < 2; ++n) gvv[bj][n] = *(const f32x4*)(gp + bj * HALF + n * 16);
; #pragma unroll
;       for (int ai = 0; ai < 2; ++ai)
; #pragma unroll
;         for (int m = 0; m < 4; ++m) {
;           const int row = brow + ai * HALF + wr * 64 + m * 16 + fr;
;           float* rp = g.X + (size_t)row * g.N + bcol + wc * 32 + 4 * fq;
;           const float* rin = g.Xlat + (size_t)row * g.N + bcol + wc * 32 + 4 * fq;
; #pragma unroll
;           for (int bj = 0; bj < 2; ++bj)
; #pragma unroll
;             for (int n = 0; n < 2; ++n) {
;               f32x4 xv = *(const f32x4*)(rin + bj * HALF + n * 16);
;               xv += gvv[bj][n] * acc[ai][bj][m][n];
;               *(f32x4*)(rp + bj * HALF + n * 16) = xv;
;             }
.LBB0_1122:
	s_lshl_b32 s2, s1, 8
	s_cmp_gt_i32 s0, 31
	s_cselect_b32 s1, 0x6000, 0
	s_add_u32 s1, s6, s1
	v_lshl_add_u32 v154, s0, 8, v194
	s_addc_u32 s26, s7, 0
	s_ashr_i32 s3, s2, 31
	v_ashrrev_i32_e32 v155, 31, v154
	s_lshl_b64 s[24:25], s[2:3], 2
	v_lshlrev_b64 v[198:199], 12, v[154:155]
	s_add_u32 s1, s1, s24
	v_lshl_add_u64 v[198:199], s[14:15], 0, v[198:199]
	s_addc_u32 s3, s26, s25
	v_lshl_add_u64 v[198:199], v[198:199], 0, s[24:25]
	s_add_u32 s2, s1, s42
	v_lshl_add_u64 v[198:199], v[198:199], 0, s[42:43]
	s_addc_u32 s3, s3, 0
	v_lshl_add_u64 v[202:203], v[198:199], 0, v[0:1]
	global_load_dwordx4 v[102:105], v0, s[2:3]
	global_load_dwordx4 v[90:93], v0, s[2:3] offset:64
	global_load_dwordx4 v[86:89], v0, s[2:3] offset:512
	global_load_dwordx4 v[50:53], v0, s[2:3] offset:576
	s_andn2_b64 vcc, exec, s[18:19]
	v_add_u32_e32 v236, 0x10, v154
	v_ashrrev_i32_e32 v237, 31, v236
	v_lshlrev_b64 v[236:237], 12, v[236:237]
	v_lshl_add_u64 v[236:237], s[14:15], 0, v[236:237]
	v_lshl_add_u64 v[236:237], v[236:237], 0, s[24:25]
	v_lshl_add_u64 v[236:237], v[236:237], 0, s[42:43]
	v_lshl_add_u64 v[236:237], v[236:237], 0, v[0:1]
	global_load_dwordx4 v[204:207], v[202:203], off
	global_load_dwordx4 v[208:211], v[202:203], off offset:64
	global_load_dwordx4 v[212:215], v[202:203], off offset:512
	global_load_dwordx4 v[216:219], v[202:203], off offset:576
	global_load_dwordx4 v[220:223], v[236:237], off
	global_load_dwordx4 v[224:227], v[236:237], off offset:64
	global_load_dwordx4 v[228:231], v[236:237], off offset:512
	global_load_dwordx4 v[232:235], v[236:237], off offset:576
	s_waitcnt vmcnt(7)
	v_pk_fma_f32 v[144:145], v[144:145], v[104:105], v[206:207]
	v_pk_fma_f32 v[142:143], v[142:143], v[102:103], v[204:205]
	global_store_dwordx4 v[202:203], v[142:145], off
	v_add_u32_e32 v238, 0x20, v154
	v_ashrrev_i32_e32 v239, 31, v238
	v_lshlrev_b64 v[238:239], 12, v[238:239]
	v_lshl_add_u64 v[238:239], s[14:15], 0, v[238:239]
	v_lshl_add_u64 v[238:239], v[238:239], 0, s[24:25]
	v_lshl_add_u64 v[238:239], v[238:239], 0, s[42:43]
	v_lshl_add_u64 v[238:239], v[238:239], 0, v[0:1]
	global_load_dwordx4 v[204:207], v[238:239], off
	s_waitcnt vmcnt(8)
	v_pk_fma_f32 v[140:141], v[140:141], v[92:93], v[210:211]
	v_pk_fma_f32 v[138:139], v[138:139], v[90:91], v[208:209]
	global_store_dwordx4 v[202:203], v[138:141], off offset:64
	global_load_dwordx4 v[208:211], v[238:239], off offset:64
	s_waitcnt vmcnt(9)
	v_pk_fma_f32 v[136:137], v[136:137], v[88:89], v[214:215]
	v_pk_fma_f32 v[134:135], v[134:135], v[86:87], v[212:213]
	global_store_dwordx4 v[202:203], v[134:137], off offset:512
	global_load_dwordx4 v[212:215], v[238:239], off offset:512
	s_waitcnt vmcnt(10)
	v_pk_fma_f32 v[132:133], v[132:133], v[52:53], v[218:219]
	v_pk_fma_f32 v[130:131], v[130:131], v[50:51], v[216:217]
	global_store_dwordx4 v[202:203], v[130:133], off offset:576
	global_load_dwordx4 v[216:219], v[238:239], off offset:576
	s_waitcnt vmcnt(11)
	v_pk_fma_f32 v[128:129], v[128:129], v[104:105], v[222:223]
	v_pk_fma_f32 v[126:127], v[126:127], v[102:103], v[220:221]
	global_store_dwordx4 v[236:237], v[126:129], off
	v_add_u32_e32 v240, 0x30, v154
	v_ashrrev_i32_e32 v241, 31, v240
	v_lshlrev_b64 v[240:241], 12, v[240:241]
	v_lshl_add_u64 v[240:241], s[14:15], 0, v[240:241]
	v_lshl_add_u64 v[240:241], v[240:241], 0, s[24:25]
	v_lshl_add_u64 v[240:241], v[240:241], 0, s[42:43]
	v_lshl_add_u64 v[240:241], v[240:241], 0, v[0:1]
	global_load_dwordx4 v[220:223], v[240:241], off
	s_waitcnt vmcnt(12)
	v_pk_fma_f32 v[124:125], v[124:125], v[92:93], v[226:227]
	v_pk_fma_f32 v[122:123], v[122:123], v[90:91], v[224:225]
	global_store_dwordx4 v[236:237], v[122:125], off offset:64
	global_load_dwordx4 v[224:227], v[240:241], off offset:64
	s_waitcnt vmcnt(13)
	v_pk_fma_f32 v[120:121], v[120:121], v[88:89], v[230:231]
	v_pk_fma_f32 v[118:119], v[118:119], v[86:87], v[228:229]
	global_store_dwordx4 v[236:237], v[118:121], off offset:512
	global_load_dwordx4 v[228:231], v[240:241], off offset:512
	s_waitcnt vmcnt(14)
	v_pk_fma_f32 v[116:117], v[116:117], v[52:53], v[234:235]
	v_pk_fma_f32 v[114:115], v[114:115], v[50:51], v[232:233]
	global_store_dwordx4 v[236:237], v[114:117], off offset:576
	global_load_dwordx4 v[232:235], v[240:241], off offset:576
	s_waitcnt vmcnt(14)
	v_pk_fma_f32 v[112:113], v[112:113], v[104:105], v[206:207]
	v_pk_fma_f32 v[110:111], v[110:111], v[102:103], v[204:205]
	global_store_dwordx4 v[238:239], v[110:113], off
	v_add_u32_e32 v236, 0x80, v154
	v_ashrrev_i32_e32 v237, 31, v236
	v_lshlrev_b64 v[236:237], 12, v[236:237]
	v_lshl_add_u64 v[236:237], s[14:15], 0, v[236:237]
	v_lshl_add_u64 v[236:237], v[236:237], 0, s[24:25]
	v_lshl_add_u64 v[236:237], v[236:237], 0, s[42:43]
	v_lshl_add_u64 v[236:237], v[236:237], 0, v[0:1]
	global_load_dwordx4 v[204:207], v[236:237], off
	s_waitcnt vmcnt(14)
	v_pk_fma_f32 v[108:109], v[108:109], v[92:93], v[210:211]
	v_pk_fma_f32 v[106:107], v[106:107], v[90:91], v[208:209]
	global_store_dwordx4 v[238:239], v[106:109], off offset:64
	global_load_dwordx4 v[208:211], v[236:237], off offset:64
	s_waitcnt vmcnt(14)
	v_pk_fma_f32 v[100:101], v[100:101], v[88:89], v[214:215]
	v_pk_fma_f32 v[98:99], v[98:99], v[86:87], v[212:213]
	global_store_dwordx4 v[238:239], v[98:101], off offset:512
	global_load_dwordx4 v[212:215], v[236:237], off offset:512
	s_waitcnt vmcnt(14)
	v_pk_fma_f32 v[96:97], v[96:97], v[52:53], v[218:219]
	v_pk_fma_f32 v[94:95], v[94:95], v[50:51], v[216:217]
	global_store_dwordx4 v[238:239], v[94:97], off offset:576
	global_load_dwordx4 v[216:219], v[236:237], off offset:576
	s_waitcnt vmcnt(14)
; #define BAR __builtin_amdgcn_s_barrier()
; DI void gemm_phase(const GemmArgs& g, char* shm_c) {
;     ...
;       for (int ai = 0; ai < 2; ++ai)
; #pragma unroll
;         for (int m = 0; m < 4; ++m) {
;           const int row = brow + ai * HALF + wr * 64 + m * 16 + fr;
;           float* rp = g.X + (size_t)row * g.N + bcol + wc * 32 + 4 * fq;
;           const float* rin = g.Xlat + (size_t)row * g.N + bcol + wc * 32 + 4 * fq;
; #pragma unroll
;           for (int bj = 0; bj < 2; ++bj)
; #pragma unroll
;             for (int n = 0; n < 2; ++n) {
;               f32x4 xv = *(const f32x4*)(rin + bj * HALF + n * 16);
;               xv += gvv[bj][n] * acc[ai][bj][m][n];
;               *(f32x4*)(rp + bj * HALF + n * 16) = xv;
;             }
;     ...
;     if (!has_next) break;
; #pragma unroll
;     for (int a = 0; a < 2; ++a)
; #pragma unroll
;       for (int b = 0; b < 2; ++b)
; #pragma unroll
;         for (int m = 0; m < 4; ++m)
; #pragma unroll
;           for (int n = 0; n < 2; ++n) acc[a][b][m][n] = (f32x4){0.f, 0.f, 0.f, 0.f};
;     tile = ntile; pm = npm; pn = npn; cA = nA; cB = nB;
;     if (wr == 1) BAR;
	v_pk_fma_f32 v[84:85], v[84:85], v[104:105], v[222:223]
	v_pk_fma_f32 v[82:83], v[82:83], v[102:103], v[220:221]
	global_store_dwordx4 v[240:241], v[82:85], off
	v_add_u32_e32 v238, 0x90, v154
	v_ashrrev_i32_e32 v239, 31, v238
	v_lshlrev_b64 v[238:239], 12, v[238:239]
	v_lshl_add_u64 v[238:239], s[14:15], 0, v[238:239]
	v_lshl_add_u64 v[238:239], v[238:239], 0, s[24:25]
	v_lshl_add_u64 v[238:239], v[238:239], 0, s[42:43]
	v_lshl_add_u64 v[238:239], v[238:239], 0, v[0:1]
	global_load_dwordx4 v[220:223], v[238:239], off
	s_waitcnt vmcnt(14)
	v_pk_fma_f32 v[80:81], v[80:81], v[92:93], v[226:227]
	v_pk_fma_f32 v[78:79], v[78:79], v[90:91], v[224:225]
	global_store_dwordx4 v[240:241], v[78:81], off offset:64
	global_load_dwordx4 v[224:227], v[238:239], off offset:64
	s_waitcnt vmcnt(14)
	v_pk_fma_f32 v[76:77], v[76:77], v[88:89], v[230:231]
	v_pk_fma_f32 v[74:75], v[74:75], v[86:87], v[228:229]
	global_store_dwordx4 v[240:241], v[74:77], off offset:512
	global_load_dwordx4 v[228:231], v[238:239], off offset:512
	s_waitcnt vmcnt(14)
	v_pk_fma_f32 v[72:73], v[72:73], v[52:53], v[234:235]
	v_pk_fma_f32 v[70:71], v[70:71], v[50:51], v[232:233]
	global_store_dwordx4 v[240:241], v[70:73], off offset:576
	global_load_dwordx4 v[232:235], v[238:239], off offset:576
	s_waitcnt vmcnt(14)
	v_pk_fma_f32 v[68:69], v[68:69], v[104:105], v[206:207]
	v_pk_fma_f32 v[66:67], v[66:67], v[102:103], v[204:205]
	global_store_dwordx4 v[236:237], v[66:69], off
	v_add_u32_e32 v240, 0xa0, v154
	v_ashrrev_i32_e32 v241, 31, v240
	v_lshlrev_b64 v[240:241], 12, v[240:241]
	v_lshl_add_u64 v[240:241], s[14:15], 0, v[240:241]
	v_lshl_add_u64 v[240:241], v[240:241], 0, s[24:25]
	v_lshl_add_u64 v[240:241], v[240:241], 0, s[42:43]
	v_lshl_add_u64 v[240:241], v[240:241], 0, v[0:1]
	global_load_dwordx4 v[204:207], v[240:241], off
	s_waitcnt vmcnt(14)
	v_pk_fma_f32 v[64:65], v[64:65], v[92:93], v[210:211]
	v_pk_fma_f32 v[62:63], v[62:63], v[90:91], v[208:209]
	global_store_dwordx4 v[236:237], v[62:65], off offset:64
	global_load_dwordx4 v[208:211], v[240:241], off offset:64
	s_waitcnt vmcnt(14)
	v_pk_fma_f32 v[60:61], v[60:61], v[88:89], v[214:215]
	v_pk_fma_f32 v[58:59], v[58:59], v[86:87], v[212:213]
	global_store_dwordx4 v[236:237], v[58:61], off offset:512
	global_load_dwordx4 v[212:215], v[240:241], off offset:512
	s_waitcnt vmcnt(14)
	v_pk_fma_f32 v[56:57], v[56:57], v[52:53], v[218:219]
	v_pk_fma_f32 v[54:55], v[54:55], v[50:51], v[216:217]
	global_store_dwordx4 v[236:237], v[54:57], off offset:576
	global_load_dwordx4 v[216:219], v[240:241], off offset:576
	s_waitcnt vmcnt(14)
	v_pk_fma_f32 v[48:49], v[48:49], v[104:105], v[222:223]
	v_pk_fma_f32 v[46:47], v[46:47], v[102:103], v[220:221]
	global_store_dwordx4 v[238:239], v[46:49], off
	v_add_u32_e32 v236, 0xb0, v154
	v_ashrrev_i32_e32 v237, 31, v236
	v_lshlrev_b64 v[236:237], 12, v[236:237]
	v_lshl_add_u64 v[236:237], s[14:15], 0, v[236:237]
	v_lshl_add_u64 v[236:237], v[236:237], 0, s[24:25]
	v_lshl_add_u64 v[236:237], v[236:237], 0, s[42:43]
	v_lshl_add_u64 v[236:237], v[236:237], 0, v[0:1]
	global_load_dwordx4 v[220:223], v[236:237], off
	s_waitcnt vmcnt(14)
	v_pk_fma_f32 v[44:45], v[44:45], v[92:93], v[226:227]
	v_pk_fma_f32 v[42:43], v[42:43], v[90:91], v[224:225]
	global_store_dwordx4 v[238:239], v[42:45], off offset:64
	global_load_dwordx4 v[224:227], v[236:237], off offset:64
	s_waitcnt vmcnt(14)
	v_pk_fma_f32 v[40:41], v[40:41], v[88:89], v[230:231]
	v_pk_fma_f32 v[38:39], v[38:39], v[86:87], v[228:229]
	global_store_dwordx4 v[238:239], v[38:41], off offset:512
	global_load_dwordx4 v[228:231], v[236:237], off offset:512
	s_waitcnt vmcnt(14)
	v_pk_fma_f32 v[24:25], v[24:25], v[52:53], v[234:235]
	v_pk_fma_f32 v[22:23], v[22:23], v[50:51], v[232:233]
	global_store_dwordx4 v[238:239], v[22:25], off offset:576
	global_load_dwordx4 v[232:235], v[236:237], off offset:576
	s_waitcnt vmcnt(14)
	v_pk_fma_f32 v[28:29], v[28:29], v[104:105], v[206:207]
	v_pk_fma_f32 v[26:27], v[26:27], v[102:103], v[204:205]
	global_store_dwordx4 v[240:241], v[26:29], off
	s_waitcnt vmcnt(13)
	v_pk_fma_f32 v[20:21], v[20:21], v[92:93], v[210:211]
	v_pk_fma_f32 v[18:19], v[18:19], v[90:91], v[208:209]
	global_store_dwordx4 v[240:241], v[18:21], off offset:64
	s_waitcnt vmcnt(12)
	v_pk_fma_f32 v[36:37], v[36:37], v[88:89], v[214:215]
	v_pk_fma_f32 v[34:35], v[34:35], v[86:87], v[212:213]
	global_store_dwordx4 v[240:241], v[34:37], off offset:512
	s_waitcnt vmcnt(11)
	v_pk_fma_f32 v[32:33], v[32:33], v[52:53], v[218:219]
	v_pk_fma_f32 v[30:31], v[30:31], v[50:51], v[216:217]
	global_store_dwordx4 v[240:241], v[30:33], off offset:576
	s_waitcnt vmcnt(10)
	v_pk_fma_f32 v[12:13], v[12:13], v[104:105], v[222:223]
	v_pk_fma_f32 v[10:11], v[10:11], v[102:103], v[220:221]
	global_store_dwordx4 v[236:237], v[10:13], off
	s_waitcnt vmcnt(9)
	v_pk_fma_f32 v[8:9], v[8:9], v[92:93], v[226:227]
	v_pk_fma_f32 v[6:7], v[6:7], v[90:91], v[224:225]
	global_store_dwordx4 v[236:237], v[6:9], off offset:64
	s_waitcnt vmcnt(8)
	v_pk_fma_f32 v[16:17], v[16:17], v[88:89], v[230:231]
	v_pk_fma_f32 v[14:15], v[14:15], v[86:87], v[228:229]
	global_store_dwordx4 v[236:237], v[14:17], off offset:512
	s_waitcnt vmcnt(7)
	v_pk_fma_f32 v[4:5], v[4:5], v[52:53], v[234:235]
	v_pk_fma_f32 v[2:3], v[2:3], v[50:51], v[232:233]
	global_store_dwordx4 v[236:237], v[2:5], off offset:576
	s_mov_b64 s[24:25], -1
	s_cbranch_vccnz .LBB0_1111
	s_andn2_b64 vcc, exec, s[16:17]
	s_cbranch_vccnz .LBB0_1110
	s_barrier
	s_branch .LBB0_1110
